# attention K staging: intra-quad sum exchanges via DPP instead of ds_bpermute
# baseline (speedup 1.0000x reference)
.LBB0_415:
	v_lshlrev_b32_e32 v116, 16, v92
	v_and_b32_e32 v108, 0xffff0000, v92
	v_lshlrev_b32_e32 v117, 16, v88
	v_and_b32_e32 v109, 0xffff0000, v88
	v_lshlrev_b32_e32 v102, 16, v93
	v_and_b32_e32 v106, 0xffff0000, v93
	v_lshlrev_b32_e32 v104, 16, v94
	v_and_b32_e32 v100, 0xffff0000, v94
	v_lshlrev_b32_e32 v92, 16, v95
	v_and_b32_e32 v88, 0xffff0000, v95
	v_mov_b32_e32 v94, v116
	v_mov_b32_e32 v95, v108
	v_lshlrev_b32_e32 v103, 16, v89
	v_and_b32_e32 v107, 0xffff0000, v89
	v_lshlrev_b32_e32 v105, 16, v90
	v_and_b32_e32 v101, 0xffff0000, v90
	v_lshlrev_b32_e32 v93, 16, v91
	v_and_b32_e32 v89, 0xffff0000, v91
	v_mov_b32_e32 v90, v117
	v_mov_b32_e32 v91, v109
	v_pk_mul_f32 v[94:95], v[94:95], v[94:95]
	v_mov_b32_e32 v98, v106
	v_mov_b32_e32 v99, v102
	v_pk_fma_f32 v[90:91], v[90:91], v[90:91], v[94:95]
	v_mov_b32_e32 v94, v107
	v_mov_b32_e32 v95, v103
	v_pk_mul_f32 v[98:99], v[98:99], v[98:99]
	v_mov_b32_e32 v118, v100
	v_pk_fma_f32 v[94:95], v[94:95], v[94:95], v[98:99]
	v_mov_b32_e32 v119, v104
	v_add_f32_e32 v90, v90, v91
	v_mov_b32_e32 v98, v101
	v_mov_b32_e32 v99, v105
	v_pk_mul_f32 v[118:119], v[118:119], v[118:119]
	v_add_f32_e32 v90, v95, v90
	v_pk_fma_f32 v[98:99], v[98:99], v[98:99], v[118:119]
	v_mov_b32_e32 v120, v88
	v_mov_b32_e32 v121, v92
	v_add_f32_e32 v90, v94, v90
	v_mov_b32_e32 v118, v89
	v_mov_b32_e32 v119, v93
	v_pk_mul_f32 v[120:121], v[120:121], v[120:121]
	v_add_f32_e32 v90, v99, v90
	v_pk_fma_f32 v[118:119], v[118:119], v[118:119], v[120:121]
	v_add_f32_e32 v90, v98, v90
	v_add_f32_e32 v90, v119, v90
	v_add_f32_e32 v90, v118, v90
	v_add_u32_e32 v94, s8, v200
	v_ashrrev_i32_e32 v95, 6, v94
	v_mov_b32_dpp v91, v90 quad_perm:[1,0,3,2] row_mask:0xf bank_mask:0xf
	v_cvt_f32_i32_e32 v95, v95
	s_cmp_gt_u32 s73, 1
	v_add_f32_e32 v90, v90, v91
	s_cselect_b64 s[58:59], -1, 0
	s_cmp_lt_u32 s73, 2
	v_mov_b32_dpp v91, v90 quad_perm:[2,3,0,1] row_mask:0xf bank_mask:0xf
	v_add_f32_e32 v90, v90, v91
	v_fmamk_f32 v90, v90, 0x3c800000, v211
	v_mul_f32_e32 v91, 0x4b800000, v90
	v_cmp_gt_f32_e32 vcc, s33, v90
	s_nop 1
	v_cndmask_b32_e32 v90, v90, v91, vcc
	v_rsq_f32_e32 v90, v90
	s_nop 0
	v_mul_f32_e32 v91, 0x45800000, v90
	v_cndmask_b32_e32 v98, v90, v91, vcc
	v_and_b32_e32 v90, 63, v94
	v_cvt_f32_ubyte0_e32 v90, v90
	v_cndmask_b32_e64 v111, v90, v95, s[4:5]
	v_pk_mul_f32 v[90:91], v[98:99], v[116:117] op_sel_hi:[0,1]
	v_mul_f32_e32 v90, v246, v90
	v_mul_f32_e32 v91, v238, v91
	s_cbranch_scc1 .LBB0_417
	v_cvt_f32_i32_e32 v94, v110
	v_mul_f32_e32 v94, 0xbf549a78, v94
	v_exp_f32_e32 v94, v94
	s_nop 0
	v_mul_f32_e32 v94, v111, v94
	v_mul_f32_e32 v95, 0.15915494, v94
	v_sin_f32_e32 v114, v95
	v_cos_f32_e32 v94, v95
	v_pk_mul_f32 v[114:115], v[114:115], v[90:91] op_sel:[0,1] op_sel_hi:[0,0]
	v_pk_mul_f32 v[116:117], v[94:95], v[90:91] op_sel_hi:[0,1]
	v_pk_fma_f32 v[90:91], v[94:95], v[90:91], v[114:115] op_sel_hi:[0,1,1] neg_lo:[0,0,1] neg_hi:[0,0,1]
	v_add_f32_e32 v90, v116, v114
